# window branch: K/V blocks of the tile staged once per workgroup in LDS by LDS-DMA (two slots, one barrier per block) instead of every wave gathering them from L1
# speedup vs baseline: 1.0037x; 1.0037x over previous
; __device__ __forceinline__ void load_k(bf16x8 (&kf)[4][2], const bf16_t* Kb, int lane) {
; #pragma unroll
;     for (int nt = 0; nt < 4; ++nt)
; #pragma unroll
;         for (int kk = 0; kk < 2; ++kk) kf[nt][kk] = *(const bf16x8*)(Kb + ((nt * 2 + kk) * 64 + lane) * 8);
; }
; __device__ __forceinline__ void load_v(bf16x8 (&vf)[4][2], const bf16_t* Vb, int lane) {
; #pragma unroll
;     for (int dt = 0; dt < 4; ++dt)
; #pragma unroll
;         for (int hh = 0; hh < 2; ++hh) vf[dt][hh] = *(const bf16x8*)(Vb + ((dt * 2 + hh) * 64 + lane) * 8);
; }
; __device__ __forceinline__ void nsa_wave(CArgs* Ap, int l, int b, int g, int tq0, const LAS float* lut, LAS float* imp, int lane) {
;     ...
;         const bf16_t* Kw = (const bf16_t*)(ws + WS_KWT) + (size_t)(b * 4 + g) * 128 * 4096;
;         const int lo = tq0 - 511, jb0 = (lo > 0 ? lo : 0) >> 6, jb1 = (tq0 + 3) >> 6;
;         for (int jb = jb0; jb <= jb1; ++jb) {
;             bf16x8 kf[4][2]; load_k(kf, Kw + (size_t)jb * 4096, lane);
;             bf16x8 vf[4][2]; load_v(vf, VWT + (size_t)jb * 4096, lane);
.LBB0_1280:
	ds_bpermute_b32 v24, v209, v215
	s_max_i32 s0, s19, 0x1ff
	s_addk_i32 s0, 0xfe01
	s_waitcnt vmcnt(5)
	v_mov_b32_e32 v39, 0
	s_lshr_b32 s72, s0, 6
	s_waitcnt lgkmcnt(0)
	v_add_f32_e32 v100, v215, v24
	ds_bpermute_b32 v101, v208, v100
	s_cmp_le_i32 s72, s21
	v_mov_b32_e32 v38, v39
	s_waitcnt vmcnt(3)
	v_mov_b32_e32 v37, v39
	v_mov_b32_e32 v36, v39
	v_mov_b32_e32 v35, v39
	v_mov_b32_e32 v34, v39
	v_mov_b32_e32 v33, v39
	v_mov_b32_e32 v32, v39
	v_mov_b32_e32 v31, v39
	v_mov_b32_e32 v30, v39
	v_mov_b32_e32 v29, v39
	v_mov_b32_e32 v28, v39
	v_mov_b32_e32 v27, v39
	v_mov_b32_e32 v26, v39
	v_mov_b32_e32 v25, v39
	v_mov_b32_e32 v24, v39
	v_mov_b32_e32 v72, v39
	s_cbranch_scc0 .LBB0_892
	v_add_u32_e32 v127, s18, v204
	s_and_b32 s1, s19, 0xffffffe0
	s_max_i32 s1, s1, 0x1ff
	s_addk_i32 s1, 0xfe01
	s_lshr_b32 s72, s1, 6
	s_add_i32 s18, s20, s17
	s_ashr_i32 s19, s18, 31
	s_add_i32 s0, s72, -1
	s_lshl_b32 s1, s72, 6
	s_lshl_b64 s[18:19], s[18:19], 20
	s_lshl_b64 s[22:23], s[72:73], 13
	s_add_u32 s18, s18, s22
	s_addc_u32 s19, s19, s23
	v_subrev_u32_e32 v102, s1, v127
	v_lshl_add_u64 v[98:99], v[90:91], 0, s[18:19]
	s_sub_i32 s25, s93, 0x10000
	s_lshr_b32 s25, s25, 13
	s_and_b32 s24, s25, 3
	s_lshl_b32 s24, s24, 11
	s_add_u32 s18, s24, 0xffffe400
	s_mov_b32 s19, -1
	s_cmp_lt_u32 s25, 4
	s_cbranch_scc1 .Lwin_ksrc
	s_add_u32 s18, s18, 0xfd200000
	s_addc_u32 s19, s19, -1
.Lwin_ksrc:
	v_mov_b32_e32 v103, 0xf149f2ca
	v_lshl_add_u64 v[98:99], v[98:99], 0, s[18:19]
	v_mov_b32_e32 v126, 0
	s_lshr_b32 s24, s25, 1
	s_lshl_b32 s24, s24, 13
	s_and_b32 s25, s25, 1
	s_lshl_b32 s25, s25, 11
	s_add_i32 s24, s24, s25
	s_add_i32 s24, s24, 0x11000
	v_lshlrev_b32_e32 v124, 4, v89
	v_add_u32_e32 v124, 0x11000, v124
	s_mov_b64 s[18:19], 0x2000
	s_waitcnt lgkmcnt(0)
	s_barrier
	s_mov_b32 m0, s24
	s_nop 0
	global_load_lds_dwordx4 v[98:99], off
	global_load_lds_dwordx4 v[98:99], off offset:1024
.Lwin_loop:
	s_waitcnt vmcnt(0)
	s_barrier
	s_add_i32 s0, s0, 1
	s_cmp_lt_i32 s0, s21
	s_cbranch_scc0 .Lwin_nokpf
	v_lshl_add_u64 v[98:99], v[98:99], 0, s[18:19]
	s_xor_b32 s24, s24, 0x8000
	s_mov_b32 m0, s24
	s_nop 0
	global_load_lds_dwordx4 v[98:99], off
	global_load_lds_dwordx4 v[98:99], off offset:1024
.Lwin_nokpf:
	ds_read_b128 v[40:43], v124
	ds_read_b128 v[44:47], v124 offset:1024
	ds_read_b128 v[48:51], v124 offset:2048
	ds_read_b128 v[52:55], v124 offset:3072
	ds_read_b128 v[56:59], v124 offset:8192
	ds_read_b128 v[60:63], v124 offset:9216
	ds_read_b128 v[64:67], v124 offset:10240
	ds_read_b128 v[68:71], v124 offset:11264
	v_mov_b32_e32 v151, 0x1cd
	v_cmp_gt_u32_e32 vcc, v151, v102
	s_cmp_eq_u64 vcc, exec
	s_cselect_b32 s17, 1, 0
	s_cbranch_scc0 .Lwin_lut_gen
	v_lshl_add_u32 v151, v102, 4, v206
	ds_read2_b32 v[244:245], v151 offset0:204 offset1:200
	ds_read2_b32 v[246:247], v151 offset0:196 offset1:192
	ds_read2_b32 v[248:249], v151 offset0:140 offset1:136
	ds_read2_b32 v[250:251], v151 offset0:132 offset1:128
	ds_read2_b32 v[252:253], v151 offset0:76 offset1:72
	ds_read2_b32 v[210:211], v151 offset0:68 offset1:64
	ds_read2_b32 v[212:213], v151 offset0:12 offset1:8
	ds_read_b32 v144, v151 offset:16
	ds_read_b32 v255, v151
	s_branch .Lwin_lut_done

; __device__ __forceinline__ void nsa_wave(CArgs* Ap, int l, int b, int g, int tq0, const LAS float* lut, LAS float* imp, int lane) {
;     ...
;         for (int jb = jb0; jb <= jb1; ++jb) {
;             bf16x8 kf[4][2]; load_k(kf, Kw + (size_t)jb * 4096, lane);
;             bf16x8 vf[4][2]; load_v(vf, VWT + (size_t)jb * 4096, lane);
;             f32x4 acc[4];
; #pragma unroll
;             for (int nt = 0; nt < 4; ++nt) acc[nt] = (f32x4){0.f, 0.f, 0.f, 0.f};
;             qk_acc(acc, kf, qB);
;             bf16x8 pB[2];
;             softmax_block<2>(acc, jb * 64, true, t, g4, lutg, st, Od, pB);
.Lwin_lut_done:
	v_subrev_u32_e32 v102, 64, v102
	s_waitcnt lgkmcnt(0)
	v_mfma_f32_16x16x32_bf16 v[228:231], v[40:43], v[0:3], 0
	v_mfma_f32_16x16x32_bf16 v[232:235], v[48:51], v[0:3], 0
	v_mfma_f32_16x16x32_bf16 v[236:239], v[56:59], v[0:3], 0
	v_mfma_f32_16x16x32_bf16 v[240:243], v[64:67], v[0:3], 0
	v_mfma_f32_16x16x32_bf16 v[228:231], v[44:47], v[4:7], v[228:231]
	v_mfma_f32_16x16x32_bf16 v[232:235], v[52:55], v[4:7], v[232:235]
	v_mfma_f32_16x16x32_bf16 v[236:239], v[60:63], v[4:7], v[236:239]
	v_mfma_f32_16x16x32_bf16 v[240:243], v[68:71], v[4:7], v[240:243]
	ds_read_b128 v[72:75], v124 offset:16384
	ds_read_b128 v[76:79], v124 offset:17408
	ds_read_b128 v[80:83], v124 offset:18432
	ds_read_b128 v[104:107], v124 offset:19456
	ds_read_b128 v[108:111], v124 offset:24576
	ds_read_b128 v[112:115], v124 offset:25600
	ds_read_b128 v[116:119], v124 offset:26624
	ds_read_b128 v[120:123], v124 offset:27648
	v_add_f32_e32 v228, v228, v244
	v_add_f32_e32 v229, v229, v245
	v_add_f32_e32 v230, v230, v246
	v_add_f32_e32 v231, v231, v247
	v_add_f32_e32 v232, v232, v248
	v_add_f32_e32 v233, v233, v249
	v_add_f32_e32 v234, v234, v250
	v_add_f32_e32 v235, v235, v251
	v_add_f32_e32 v236, v236, v252
	v_add_f32_e32 v237, v237, v253
	v_add_f32_e32 v238, v238, v210
	v_add_f32_e32 v239, v239, v211
	v_add_f32_e32 v240, v240, v212
	v_add_f32_e32 v241, v241, v213
	v_add_f32_e32 v242, v242, v144
	v_add_f32_e32 v243, v243, v255
	s_cmp_lg_u32 s17, 0
	s_cbranch_scc0 .Lwin_sm_gen
	v_max3_f32 v244, v228, v229, v230
	v_max3_f32 v247, v231, v232, v233
	v_max3_f32 v250, v234, v235, v236
	v_max3_f32 v253, v237, v238, v239
	v_max3_f32 v212, v240, v241, v242
	v_max3_f32 v244, v244, v247, v250
	v_max3_f32 v253, v253, v212, v243
	v_max_f32_e32 v244, v244, v253
	v_mov_b32_e32 v127, v244
	s_nop 1
	v_permlane16_swap_b32_e32 v244, v127
	v_max_f32_e32 v244, v244, v127
	v_mov_b32_e32 v127, v244
	s_nop 1
	v_permlane32_swap_b32_e32 v244, v127
	v_max3_f32 v214, v103, v244, v127
	v_sub_f32_e32 v150, v103, v214
	v_sub_f32_e32 v228, v228, v214
	v_sub_f32_e32 v229, v229, v214
	v_sub_f32_e32 v230, v230, v214
	v_sub_f32_e32 v231, v231, v214
	v_sub_f32_e32 v232, v232, v214
	v_sub_f32_e32 v233, v233, v214
	v_sub_f32_e32 v234, v234, v214
	v_sub_f32_e32 v235, v235, v214
	v_sub_f32_e32 v236, v236, v214
	v_sub_f32_e32 v237, v237, v214
	v_sub_f32_e32 v238, v238, v214
	v_sub_f32_e32 v239, v239, v214
	v_sub_f32_e32 v240, v240, v214
	v_sub_f32_e32 v241, v241, v214
	v_sub_f32_e32 v242, v242, v214
	v_sub_f32_e32 v243, v243, v214
	v_mul_f32_e32 v150, 0x3fb8aa3b, v150
	v_mul_f32_e32 v228, 0x3fb8aa3b, v228
	v_mul_f32_e32 v229, 0x3fb8aa3b, v229
	v_mul_f32_e32 v230, 0x3fb8aa3b, v230
	v_mul_f32_e32 v231, 0x3fb8aa3b, v231
	v_mul_f32_e32 v232, 0x3fb8aa3b, v232
	v_mul_f32_e32 v233, 0x3fb8aa3b, v233
	v_mul_f32_e32 v234, 0x3fb8aa3b, v234
	v_mul_f32_e32 v235, 0x3fb8aa3b, v235
	v_mul_f32_e32 v236, 0x3fb8aa3b, v236
	v_mul_f32_e32 v237, 0x3fb8aa3b, v237
	v_mul_f32_e32 v238, 0x3fb8aa3b, v238
	v_mul_f32_e32 v239, 0x3fb8aa3b, v239
	v_mul_f32_e32 v240, 0x3fb8aa3b, v240
	v_mul_f32_e32 v241, 0x3fb8aa3b, v241
	v_mul_f32_e32 v242, 0x3fb8aa3b, v242
	v_mul_f32_e32 v243, 0x3fb8aa3b, v243
	v_exp_f32_e32 v150, v150
	v_exp_f32_e32 v228, v228
	v_exp_f32_e32 v229, v229
	v_exp_f32_e32 v230, v230
	v_exp_f32_e32 v231, v231
	v_exp_f32_e32 v232, v232
	v_exp_f32_e32 v233, v233
	v_exp_f32_e32 v234, v234
	v_exp_f32_e32 v235, v235
	v_exp_f32_e32 v236, v236
	v_exp_f32_e32 v237, v237
	v_exp_f32_e32 v238, v238
	v_exp_f32_e32 v239, v239
	v_exp_f32_e32 v240, v240
	v_exp_f32_e32 v241, v241
	v_exp_f32_e32 v242, v242
	v_exp_f32_e32 v243, v243
	v_mov_b32_e32 v103, v214
	s_branch .Lwin_sm_done

; __device__ __forceinline__ unsigned pk2(float lo, float hi) { return pg8::cvt_pk_bf16(lo, hi); }
; template <int MODE>
; __device__ __forceinline__ void softmax_block(f32x4 (&acc)[4], int base, bool ok, int t, int g4, const LAS float* lutg, SmState& st, f32x4 (&O)[4], bf16x8 (&pB)[2]) {
;     ...
;     st.l = st.l * sc + ls; st.m = mn;
; #pragma unroll
;     for (int dt = 0; dt < 4; ++dt) O[dt] = O[dt] * sc;
; #pragma unroll
;     for (int hh = 0; hh < 2; ++hh) { u32x4 w; w.x = pk2(acc[2 * hh][0], acc[2 * hh][1]); w.y = pk2(acc[2 * hh][2], acc[2 * hh][3]); w.z = pk2(acc[2 * hh + 1][0], acc[2 * hh + 1][1]); w.w = pk2(acc[2 * hh + 1][2], acc[2 * hh + 1][3]);
;         pB[hh] = __builtin_bit_cast(bf16x8, w); }
; __device__ __forceinline__ void nsa_wave(CArgs* Ap, int l, int b, int g, int tq0, const LAS float* lut, LAS float* imp, int lane) {
;     ...
;             softmax_block<2>(acc, jb * 64, true, t, g4, lutg, st, Od, pB);
;             pv_acc(Od, vf, pB);
;         }
.Lwin_sm_done:
	v_pk_mul_f32 v[38:39], v[38:39], v[150:151] op_sel_hi:[1,0]
	v_pk_mul_f32 v[36:37], v[36:37], v[150:151] op_sel_hi:[1,0]
	v_pk_mul_f32 v[34:35], v[34:35], v[150:151] op_sel_hi:[1,0]
	v_pk_mul_f32 v[32:33], v[32:33], v[150:151] op_sel_hi:[1,0]
	v_pk_mul_f32 v[30:31], v[30:31], v[150:151] op_sel_hi:[1,0]
	v_pk_mul_f32 v[28:29], v[28:29], v[150:151] op_sel_hi:[1,0]
	v_pk_mul_f32 v[26:27], v[26:27], v[150:151] op_sel_hi:[1,0]
	v_pk_mul_f32 v[24:25], v[24:25], v[150:151] op_sel_hi:[1,0]
	v_add_f32_e32 v127, v229, v228
	v_add_f32_e32 v127, v230, v127
	v_add_f32_e32 v127, v231, v127
	v_add_f32_e32 v127, v232, v127
	v_add_f32_e32 v127, v233, v127
	v_add_f32_e32 v127, v234, v127
	v_add_f32_e32 v127, v235, v127
	v_add_f32_e32 v127, v236, v127
	v_add_f32_e32 v127, v237, v127
	v_add_f32_e32 v127, v238, v127
	v_add_f32_e32 v127, v239, v127
	v_add_f32_e32 v127, v240, v127
	v_add_f32_e32 v127, v241, v127
	v_add_f32_e32 v127, v242, v127
	v_add_f32_e32 v127, v243, v127
	v_fmac_f32_e32 v127, v126, v150
	v_cvt_pk_bf16_f32 v244, v228, v229
	v_cvt_pk_bf16_f32 v245, v230, v231
	v_cvt_pk_bf16_f32 v246, v232, v233
	v_cvt_pk_bf16_f32 v247, v234, v235
	v_cvt_pk_bf16_f32 v248, v236, v237
	v_cvt_pk_bf16_f32 v249, v238, v239
	v_cvt_pk_bf16_f32 v250, v240, v241
	v_cvt_pk_bf16_f32 v251, v242, v243
	v_mov_b32_e32 v126, v127
	s_waitcnt lgkmcnt(0)
	s_nop 0
	v_mfma_f32_16x16x32_bf16 v[36:39], v[72:75], v[244:247], v[36:39]
	v_mfma_f32_16x16x32_bf16 v[32:35], v[80:83], v[244:247], v[32:35]
	v_mfma_f32_16x16x32_bf16 v[28:31], v[108:111], v[244:247], v[28:31]
	v_mfma_f32_16x16x32_bf16 v[24:27], v[116:119], v[244:247], v[24:27]
	v_mfma_f32_16x16x32_bf16 v[36:39], v[76:79], v[248:251], v[36:39]
	v_mfma_f32_16x16x32_bf16 v[32:35], v[104:107], v[248:251], v[32:35]
	v_mfma_f32_16x16x32_bf16 v[28:31], v[112:115], v[248:251], v[28:31]
	v_mfma_f32_16x16x32_bf16 v[24:27], v[120:123], v[248:251], v[24:27]
	v_xor_b32_e32 v124, 0x8000, v124
	s_cmp_lt_i32 s0, s21
	s_cbranch_scc1 .Lwin_loop
.Lwin_last:
	s_barrier
	v_mov_b32_e32 v72, v126
	s_branch .LBB0_892
